# e16: dm_gen + fast wo2_convert relocated to the 224 WGs idle in P5's 5th-round tail (after their rec_w_in conversion), on top of e14+e15
# baseline (speedup 1.0000x reference)
.LBB0_1000:
	s_cmp_gt_u32 s2, 31
	s_cbranch_scc0 .Le13_cont
	v_writelane_b32 v254, s4, 27
	v_writelane_b32 v254, s5, 28
	v_writelane_b32 v254, s16, 29
	v_writelane_b32 v254, s18, 30
	v_writelane_b32 v254, s19, 31
	v_writelane_b32 v254, s21, 32
	v_writelane_b32 v254, s23, 33
	v_writelane_b32 v254, s24, 34
	v_writelane_b32 v254, s25, 35
	v_writelane_b32 v254, s28, 36
	s_movk_i32 s99, 0x5a5a
	s_add_i32 s21, s2, 0xffffffe0
	s_branch .Le13_dm_entry

.Le13_dm_entry:
	s_bitcmp1_b32 s90, 2
	s_cbranch_scc1 .LBB0_1373
	s_cmpk_gt_i32 s2, 0x20bf
	s_cbranch_scc1 .LBB0_1373
	s_mul_i32 s4, s21, 0x2100
	s_mul_hi_i32 s5, s21, 0x2100
	s_add_u32 s4, s92, s4
	s_waitcnt vmcnt(0)
	v_lshlrev_b32_e32 v2, 4, v0
	v_mov_b32_e32 v3, 0
	s_addc_u32 s5, s93, s5
	s_movk_i32 s0, 0x210
	v_lshl_add_u64 v[2:3], s[4:5], 0, v[2:3]
	s_mov_b64 s[4:5], 0x11200000
	v_lshlrev_b32_e32 v1, 3, v0
	v_cmp_gt_u32_e64 s[0:1], s0, v0
	v_lshl_add_u64 v[2:3], v[2:3], 0, s[4:5]
	v_or_b32_e32 v6, 7, v1
	v_or_b32_e32 v7, 1, v1
	s_add_i32 s22, s21, 0x1000
	v_or_b32_e32 v8, 2, v1
	v_or_b32_e32 v9, 3, v1
	v_or_b32_e32 v10, 4, v1
	v_or_b32_e32 v11, 5, v1
	v_or_b32_e32 v12, 6, v1
	s_movk_i32 s23, 0xfff
	s_movk_i32 s24, 0x201
	s_movk_i32 s25, 0x200
	s_movk_i32 s26, 0x1001
	s_mov_b64 s[6:7], 0x2000
	s_mov_b64 s[8:9], 0x1ce000
	s_branch .LBB0_1338
.LBB0_1337:
	s_or_b64 exec, exec, s[10:11]
	s_add_i32 s4, s21, 224
	s_add_i32 s22, s22, 224
	v_lshl_add_u64 v[2:3], v[2:3], 0, s[8:9]
	s_cmpk_gt_i32 s21, 0x1f1f
	s_mov_b32 s21, s4
	s_cbranch_scc1 .LBB0_1373

.LBB0_1373:
	s_lshl_b32 s0, s2, 3
	s_add_i32 s0, s0, s33
	s_add_i32 s8, s0, 0xffffff00
	s_cmpk_gt_i32 s8, 0x1fff
	s_waitcnt vmcnt(0)
	s_barrier
	s_cbranch_scc1 .LBB0_1408
	s_mul_i32 s0, s33, 0x2100
	s_add_i32 s4, s0, 0
	v_lshrrev_b32_e32 v8, 5, v162
	s_movk_i32 s0, 0x84
	v_mov_b32_e32 v2, 0x210
	v_mad_u32_u24 v43, v8, s0, v2
	v_mov_b32_e32 v2, 0x420
	v_mad_u32_u24 v44, v8, s0, v2
	v_mov_b32_e32 v2, 0x630
	v_mad_u32_u24 v45, v8, s0, v2
	v_mov_b32_e32 v2, 0x840
	v_mad_u32_u24 v46, v8, s0, v2
	v_lshlrev_b32_e32 v2, 3, v0
	v_and_b32_e32 v2, 56, v2
	v_and_b32_e32 v1, 31, v0
	v_lshrrev_b32_e32 v40, 3, v162
	v_mul_u32_u24_e32 v41, 0x84, v2
	v_lshlrev_b32_e32 v2, 1, v2
	v_mov_b32_e32 v3, 0
	v_lshl_add_u32 v6, v1, 2, s4
	v_mul_u32_u24_e32 v7, 0x84, v8
	v_lshl_add_u64 v[4:5], s[92:93], 0, v[2:3]
	s_mov_b64 s[0:1], 0xf200000
	v_lshlrev_b32_e32 v2, 2, v40
	v_or_b32_e32 v9, 2, v8
	v_or_b32_e32 v10, 4, v8
	v_or_b32_e32 v11, 6, v8
	v_or_b32_e32 v12, 8, v8
	v_or_b32_e32 v13, 10, v8
	v_or_b32_e32 v14, 12, v8
	v_or_b32_e32 v15, 14, v8
	v_or_b32_e32 v16, 16, v8
	v_or_b32_e32 v17, 18, v8
	v_or_b32_e32 v18, 20, v8
	v_or_b32_e32 v19, 22, v8
	v_or_b32_e32 v20, 24, v8
	v_or_b32_e32 v21, 26, v8
	v_or_b32_e32 v22, 28, v8
	v_or_b32_e32 v23, 30, v8
	v_or_b32_e32 v24, 32, v8
	v_or_b32_e32 v25, 34, v8
	v_or_b32_e32 v26, 36, v8
	v_or_b32_e32 v27, 38, v8
	v_or_b32_e32 v28, 40, v8
	v_or_b32_e32 v29, 42, v8
	v_or_b32_e32 v30, 44, v8
	v_or_b32_e32 v31, 46, v8
	v_or_b32_e32 v32, 48, v8
	v_or_b32_e32 v33, 50, v8
	v_or_b32_e32 v34, 52, v8
	v_or_b32_e32 v35, 54, v8
	v_or_b32_e32 v36, 56, v8
	v_or_b32_e32 v37, 58, v8
	v_or_b32_e32 v38, 60, v8
	v_or_b32_e32 v39, 62, v8
	v_lshl_add_u64 v[4:5], v[4:5], 0, s[0:1]
	v_add3_u32 v41, s4, v41, v2
	s_lshl_b32 s9, s8, 5
	v_add_u32_e32 v42, v6, v7
	v_add_u32_e32 v43, v6, v43
	v_add_u32_e32 v44, v6, v44
	v_add_u32_e32 v45, v6, v45
	v_add_u32_e32 v46, v6, v46
	s_branch .LBB0_1376
.Le14_rd:
	s_waitcnt lgkmcnt(0)
	s_sub_i32 s4, 0, s1
	ds_read2_b32 v[6:7], v41 offset1:33
	s_add_i32 s4, s4, s9
	s_waitcnt lgkmcnt(0)
	v_cvt_pk_bf16_f32 v48, v6, v7
	ds_read2_b32 v[6:7], v41 offset0:66 offset1:99
	v_add_u32_e32 v54, s4, v40
	s_waitcnt lgkmcnt(0)
	v_cvt_pk_bf16_f32 v49, v6, v7
	ds_read2_b32 v[6:7], v41 offset0:132 offset1:165
	s_ashr_i32 s1, s0, 31
	v_ashrrev_i32_e32 v55, 31, v54
	s_waitcnt lgkmcnt(0)
	v_cvt_pk_bf16_f32 v50, v6, v7
	ds_read2_b32 v[6:7], v41 offset0:198 offset1:231
	v_lshl_add_u64 v[52:53], s[0:1], 1, v[4:5]
	v_lshlrev_b64 v[56:57], 13, v[54:55]
	s_waitcnt lgkmcnt(0)
	v_cvt_pk_bf16_f32 v51, v6, v7
	ds_read2_b32 v[6:7], v41 offset0:8 offset1:41
	v_lshl_add_u64 v[56:57], v[52:53], 0, v[56:57]
	global_store_dwordx4 v[56:57], v[48:51], off
	v_add_u32_e32 v56, 8, v54
	v_ashrrev_i32_e32 v57, 31, v56
	s_waitcnt lgkmcnt(0)
	v_cvt_pk_bf16_f32 v48, v6, v7
	ds_read2_b32 v[6:7], v41 offset0:74 offset1:107
	s_waitcnt lgkmcnt(0)
	v_cvt_pk_bf16_f32 v49, v6, v7
	ds_read2_b32 v[6:7], v41 offset0:140 offset1:173
	s_waitcnt lgkmcnt(0)
	v_cvt_pk_bf16_f32 v50, v6, v7
	ds_read2_b32 v[6:7], v41 offset0:206 offset1:239
	v_lshlrev_b64 v[56:57], 13, v[56:57]
	s_waitcnt lgkmcnt(0)
	v_cvt_pk_bf16_f32 v51, v6, v7
	ds_read2_b32 v[6:7], v41 offset0:16 offset1:49
	v_lshl_add_u64 v[56:57], v[52:53], 0, v[56:57]
	global_store_dwordx4 v[56:57], v[48:51], off
	v_add_u32_e32 v56, 16, v54
	v_ashrrev_i32_e32 v57, 31, v56
	s_waitcnt lgkmcnt(0)
	v_cvt_pk_bf16_f32 v48, v6, v7
	ds_read2_b32 v[6:7], v41 offset0:82 offset1:115
	s_waitcnt lgkmcnt(0)
	v_cvt_pk_bf16_f32 v49, v6, v7
	ds_read2_b32 v[6:7], v41 offset0:148 offset1:181
	s_waitcnt lgkmcnt(0)
	v_cvt_pk_bf16_f32 v50, v6, v7
	ds_read2_b32 v[6:7], v41 offset0:214 offset1:247
	v_lshlrev_b64 v[56:57], 13, v[56:57]
	v_add_u32_e32 v54, 24, v54
	s_waitcnt lgkmcnt(0)
	v_cvt_pk_bf16_f32 v51, v6, v7
	ds_read2_b32 v[6:7], v41 offset0:24 offset1:57
	v_lshl_add_u64 v[56:57], v[52:53], 0, v[56:57]
	v_ashrrev_i32_e32 v55, 31, v54
	global_store_dwordx4 v[56:57], v[48:51], off
	v_lshlrev_b64 v[54:55], 13, v[54:55]
	v_lshl_add_u64 v[52:53], v[52:53], 0, v[54:55]
	s_waitcnt lgkmcnt(0)
	v_cvt_pk_bf16_f32 v48, v6, v7
	ds_read2_b32 v[6:7], v41 offset0:90 offset1:123
	s_waitcnt lgkmcnt(0)
	v_cvt_pk_bf16_f32 v49, v6, v7
	ds_read2_b32 v[6:7], v41 offset0:156 offset1:189
	s_waitcnt lgkmcnt(0)
	v_cvt_pk_bf16_f32 v50, v6, v7
	ds_read2_b32 v[6:7], v41 offset0:222 offset1:255
	s_waitcnt lgkmcnt(0)
	v_cvt_pk_bf16_f32 v51, v6, v7
	global_store_dwordx4 v[52:53], v[48:51], off
	s_waitcnt lgkmcnt(0)
	s_add_i32 s0, s8, 0x700
	v_add_u32_e32 v40, 0xe000, v40
	v_add_u32_e32 v1, 0xe000, v1
	s_cmpk_lt_i32 s8, 0x1900
	s_mov_b32 s8, s0
	s_cbranch_scc0 .LBB0_1408
.LBB0_1376:
	s_ashr_i32 s0, s8, 31
	s_lshr_b32 s0, s0, 25
	s_add_i32 s0, s8, s0
	s_ashr_i32 s1, s0, 7
	s_lshl_b32 s0, s1, 6
	s_lshl_b32 s1, s1, 12
	s_sub_i32 s10, s9, s1
	v_add_u32_e32 v2, s10, v1
	s_lshl_b32 s4, s0, 14
	v_lshlrev_b32_e32 v196, 2, v2
	s_add_u32 s6, s82, s4
	v_lshl_add_u32 v196, v8, 14, v196
	s_addc_u32 s7, s83, 0
	v_mov_b32_e32 v197, v42
	global_load_dword v164, v196, s[6:7] nt
	v_add_u32_e32 v196, 0x8000, v196
	global_load_dword v165, v196, s[6:7] nt
	v_add_u32_e32 v196, 0x8000, v196
	global_load_dword v166, v196, s[6:7] nt
	v_add_u32_e32 v196, 0x8000, v196
	global_load_dword v167, v196, s[6:7] nt
	v_add_u32_e32 v196, 0x8000, v196
	global_load_dword v168, v196, s[6:7] nt
	v_add_u32_e32 v196, 0x8000, v196
	global_load_dword v169, v196, s[6:7] nt
	v_add_u32_e32 v196, 0x8000, v196
	global_load_dword v170, v196, s[6:7] nt
	v_add_u32_e32 v196, 0x8000, v196
	global_load_dword v171, v196, s[6:7] nt
	v_add_u32_e32 v196, 0x8000, v196
	global_load_dword v172, v196, s[6:7] nt
	v_add_u32_e32 v196, 0x8000, v196
	global_load_dword v173, v196, s[6:7] nt
	v_add_u32_e32 v196, 0x8000, v196
	global_load_dword v174, v196, s[6:7] nt
	v_add_u32_e32 v196, 0x8000, v196
	global_load_dword v175, v196, s[6:7] nt
	v_add_u32_e32 v196, 0x8000, v196
	global_load_dword v176, v196, s[6:7] nt
	v_add_u32_e32 v196, 0x8000, v196
	global_load_dword v177, v196, s[6:7] nt
	v_add_u32_e32 v196, 0x8000, v196
	global_load_dword v178, v196, s[6:7] nt
	v_add_u32_e32 v196, 0x8000, v196
	global_load_dword v179, v196, s[6:7] nt
	v_add_u32_e32 v196, 0x8000, v196
	global_load_dword v180, v196, s[6:7] nt
	v_add_u32_e32 v196, 0x8000, v196
	global_load_dword v181, v196, s[6:7] nt
	v_add_u32_e32 v196, 0x8000, v196
	global_load_dword v182, v196, s[6:7] nt
	v_add_u32_e32 v196, 0x8000, v196
	global_load_dword v183, v196, s[6:7] nt
	v_add_u32_e32 v196, 0x8000, v196
	global_load_dword v184, v196, s[6:7] nt
	v_add_u32_e32 v196, 0x8000, v196
	global_load_dword v185, v196, s[6:7] nt
	v_add_u32_e32 v196, 0x8000, v196
	global_load_dword v186, v196, s[6:7] nt
	v_add_u32_e32 v196, 0x8000, v196
	global_load_dword v187, v196, s[6:7] nt
	v_add_u32_e32 v196, 0x8000, v196
	global_load_dword v188, v196, s[6:7] nt
	v_add_u32_e32 v196, 0x8000, v196
	global_load_dword v189, v196, s[6:7] nt
	v_add_u32_e32 v196, 0x8000, v196
	global_load_dword v190, v196, s[6:7] nt
	v_add_u32_e32 v196, 0x8000, v196
	global_load_dword v191, v196, s[6:7] nt
	v_add_u32_e32 v196, 0x8000, v196
	global_load_dword v192, v196, s[6:7] nt
	v_add_u32_e32 v196, 0x8000, v196
	global_load_dword v193, v196, s[6:7] nt
	v_add_u32_e32 v196, 0x8000, v196
	global_load_dword v194, v196, s[6:7] nt
	v_add_u32_e32 v196, 0x8000, v196
	global_load_dword v195, v196, s[6:7] nt
	s_waitcnt vmcnt(30)
	ds_write2_b32 v197, v164, v165 offset1:66
	s_waitcnt vmcnt(28)
	ds_write2_b32 v197, v166, v167 offset0:132 offset1:198
	v_add_u32_e32 v197, 0x420, v197
	s_waitcnt vmcnt(26)
	ds_write2_b32 v197, v168, v169 offset1:66
	s_waitcnt vmcnt(24)
	ds_write2_b32 v197, v170, v171 offset0:132 offset1:198
	v_add_u32_e32 v197, 0x420, v197
	s_waitcnt vmcnt(22)
	ds_write2_b32 v197, v172, v173 offset1:66
	s_waitcnt vmcnt(20)
	ds_write2_b32 v197, v174, v175 offset0:132 offset1:198
	v_add_u32_e32 v197, 0x420, v197
	s_waitcnt vmcnt(18)
	ds_write2_b32 v197, v176, v177 offset1:66
	s_waitcnt vmcnt(16)
	ds_write2_b32 v197, v178, v179 offset0:132 offset1:198
	v_add_u32_e32 v197, 0x420, v197
	s_waitcnt lgkmcnt(0)
	s_waitcnt vmcnt(14)
	ds_write2_b32 v197, v180, v181 offset1:66
	s_waitcnt vmcnt(12)
	ds_write2_b32 v197, v182, v183 offset0:132 offset1:198
	v_add_u32_e32 v197, 0x420, v197
	s_waitcnt vmcnt(10)
	ds_write2_b32 v197, v184, v185 offset1:66
	s_waitcnt vmcnt(8)
	ds_write2_b32 v197, v186, v187 offset0:132 offset1:198
	v_add_u32_e32 v197, 0x420, v197
	s_waitcnt vmcnt(6)
	ds_write2_b32 v197, v188, v189 offset1:66
	s_waitcnt vmcnt(4)
	ds_write2_b32 v197, v190, v191 offset0:132 offset1:198
	v_add_u32_e32 v197, 0x420, v197
	s_waitcnt vmcnt(2)
	ds_write2_b32 v197, v192, v193 offset1:66
	s_waitcnt vmcnt(0)
	ds_write2_b32 v197, v194, v195 offset0:132 offset1:198
	s_branch .Le14_rd
.LBB0_1408:
	s_cmpk_eq_u32 s99, 0x5a5a
	s_cbranch_scc0 .Le13_norm
	s_mov_b32 s99, 0
	s_waitcnt vmcnt(0) lgkmcnt(0)
	v_readlane_b32 s4, v254, 27
	v_readlane_b32 s5, v254, 28
	v_readlane_b32 s16, v254, 29
	v_readlane_b32 s18, v254, 30
	v_readlane_b32 s19, v254, 31
	v_readlane_b32 s21, v254, 32
	v_readlane_b32 s23, v254, 33
	v_readlane_b32 s24, v254, 34
	v_readlane_b32 s25, v254, 35
	v_readlane_b32 s28, v254, 36
	s_nop 4
	s_branch .Le13_cont
